# attention: the first V fragments are requested after the last QK MFMA instead of inside the QK phase (LDS reads of the QK phase are K only)
# speedup vs baseline: 1.0163x; 1.0013x over previous
.Lat_skipld:
	s_waitcnt lgkmcnt(3)
	v_mfma_f32_32x32x16_bf16 v[64:79], v[236:239], v[136:139], v[64:79]
	v_mfma_f32_32x32x16_bf16 v[96:111], v[236:239], v[160:163], v[96:111]
	ds_read_b128 v[236:239], v235 offset:128
	s_waitcnt lgkmcnt(3)
	v_mfma_f32_32x32x16_bf16 v[80:95], v[240:243], v[136:139], v[80:95]
	v_mfma_f32_32x32x16_bf16 v[112:127], v[240:243], v[160:163], v[112:127]
	ds_read_b128 v[240:243], v235 offset:6784
	s_waitcnt lgkmcnt(3)
	v_mfma_f32_32x32x16_bf16 v[64:79], v[244:247], v[140:143], v[64:79]
	v_mfma_f32_32x32x16_bf16 v[96:111], v[244:247], v[164:167], v[96:111]
	ds_read_b128 v[244:247], v235 offset:160
	s_waitcnt lgkmcnt(3)
	v_mfma_f32_32x32x16_bf16 v[80:95], v[248:251], v[140:143], v[80:95]
	v_mfma_f32_32x32x16_bf16 v[112:127], v[248:251], v[164:167], v[112:127]
	ds_read_b128 v[248:251], v235 offset:6816
	s_waitcnt lgkmcnt(3)
	v_mfma_f32_32x32x16_bf16 v[64:79], v[236:239], v[144:147], v[64:79]
	v_mfma_f32_32x32x16_bf16 v[96:111], v[236:239], v[168:171], v[96:111]
	s_waitcnt lgkmcnt(2)
	v_mfma_f32_32x32x16_bf16 v[80:95], v[240:243], v[144:147], v[80:95]
	v_mfma_f32_32x32x16_bf16 v[112:127], v[240:243], v[168:171], v[112:127]
	s_waitcnt lgkmcnt(1)
	v_mfma_f32_32x32x16_bf16 v[64:79], v[244:247], v[148:151], v[64:79]
	v_mfma_f32_32x32x16_bf16 v[96:111], v[244:247], v[172:175], v[96:111]
	s_waitcnt lgkmcnt(0)
	v_mfma_f32_32x32x16_bf16 v[80:95], v[248:251], v[148:151], v[80:95]
	v_mfma_f32_32x32x16_bf16 v[112:127], v[248:251], v[172:175], v[112:127]
	ds_read_b128 v[236:239], v218 offset:13312
	ds_read_b128 v[240:243], v218 offset:17920
	ds_read_b128 v[244:247], v218 offset:13344
	ds_read_b128 v[248:251], v218 offset:17952
	s_nop 7
	s_nop 1
	v_max3_f32 v214, v64, v65, v66
	v_max3_f32 v215, v80, v81, v82
	v_max3_f32 v216, v96, v97, v98
	v_max3_f32 v217, v112, v113, v114
	v_max3_f32 v214, v214, v67, v68
	v_max3_f32 v215, v215, v83, v84
	v_max3_f32 v216, v216, v99, v100
	v_max3_f32 v217, v217, v115, v116
	v_max3_f32 v214, v214, v69, v70
	v_max3_f32 v215, v215, v85, v86
	v_max3_f32 v216, v216, v101, v102
	v_max3_f32 v217, v217, v117, v118
	v_max3_f32 v214, v214, v71, v72
	v_max3_f32 v215, v215, v87, v88
	v_max3_f32 v216, v216, v103, v104
	v_max3_f32 v217, v217, v119, v120
	v_max3_f32 v214, v214, v73, v74
	v_max3_f32 v215, v215, v89, v90
	v_max3_f32 v216, v216, v105, v106
	v_max3_f32 v217, v217, v121, v122
	v_max3_f32 v214, v214, v75, v76
	v_max3_f32 v215, v215, v91, v92
	v_max3_f32 v216, v216, v107, v108
	v_max3_f32 v217, v217, v123, v124
	v_max3_f32 v214, v214, v77, v78
	v_max3_f32 v215, v215, v93, v94
	v_max3_f32 v216, v216, v109, v110
	v_max3_f32 v217, v217, v125, v126
	v_max_f32_e32 v214, v214, v79
	v_max_f32_e32 v215, v215, v95
	v_max_f32_e32 v216, v216, v111
	v_max_f32_e32 v217, v217, v127
	v_max_f32_e32 v214, v214, v215
	v_max_f32_e32 v216, v216, v217
	v_mov_b32_e32 v215, v214
	v_mov_b32_e32 v217, v216
	s_nop 1
	v_permlane32_swap_b32 v214, v215
	v_permlane32_swap_b32 v216, v217
	v_max_f32_e32 v214, v214, v215
	v_max_f32_e32 v216, v216, v217
	v_cmp_lt_f32_e32 vcc, s56, v214
	s_cbranch_vccz .Lat_nr0
	v_max_f32_e32 v215, 0, v214
	v_sub_f32_e32 v196, 0, v215
	v_exp_f32_e32 v196, v196
	v_add_f32_e32 v233, v233, v215
	s_nop 0
	v_mul_f32_e32 v202, v196, v202
	v_mul_f32_e32 v0, v196, v0
	v_mul_f32_e32 v1, v196, v1
	v_mul_f32_e32 v2, v196, v2
	v_mul_f32_e32 v3, v196, v3
	v_mul_f32_e32 v4, v196, v4
	v_mul_f32_e32 v5, v196, v5
	v_mul_f32_e32 v6, v196, v6
	v_mul_f32_e32 v7, v196, v7
	v_mul_f32_e32 v8, v196, v8
	v_mul_f32_e32 v9, v196, v9
	v_mul_f32_e32 v10, v196, v10
	v_mul_f32_e32 v11, v196, v11
	v_mul_f32_e32 v12, v196, v12
	v_mul_f32_e32 v13, v196, v13
	v_mul_f32_e32 v14, v196, v14
	v_mul_f32_e32 v15, v196, v15
	v_mul_f32_e32 v16, v196, v16
	v_mul_f32_e32 v17, v196, v17
	v_mul_f32_e32 v18, v196, v18
	v_mul_f32_e32 v19, v196, v19
	v_mul_f32_e32 v20, v196, v20
	v_mul_f32_e32 v21, v196, v21
	v_mul_f32_e32 v22, v196, v22
	v_mul_f32_e32 v23, v196, v23
	v_mul_f32_e32 v24, v196, v24
	v_mul_f32_e32 v25, v196, v25
	v_mul_f32_e32 v26, v196, v26
	v_mul_f32_e32 v27, v196, v27
	v_mul_f32_e32 v28, v196, v28
	v_mul_f32_e32 v29, v196, v29
	v_mul_f32_e32 v30, v196, v30
	v_mul_f32_e32 v31, v196, v31
	v_sub_f32_e32 v64, v64, v215
	v_sub_f32_e32 v65, v65, v215
	v_sub_f32_e32 v66, v66, v215
	v_sub_f32_e32 v67, v67, v215
	v_sub_f32_e32 v68, v68, v215
	v_sub_f32_e32 v69, v69, v215
	v_sub_f32_e32 v70, v70, v215
	v_sub_f32_e32 v71, v71, v215
	v_sub_f32_e32 v72, v72, v215
	v_sub_f32_e32 v73, v73, v215
	v_sub_f32_e32 v74, v74, v215
	v_sub_f32_e32 v75, v75, v215
	v_sub_f32_e32 v76, v76, v215
	v_sub_f32_e32 v77, v77, v215
	v_sub_f32_e32 v78, v78, v215
	v_sub_f32_e32 v79, v79, v215
	v_sub_f32_e32 v80, v80, v215
	v_sub_f32_e32 v81, v81, v215
	v_sub_f32_e32 v82, v82, v215
	v_sub_f32_e32 v83, v83, v215
	v_sub_f32_e32 v84, v84, v215
	v_sub_f32_e32 v85, v85, v215
	v_sub_f32_e32 v86, v86, v215
	v_sub_f32_e32 v87, v87, v215
	v_sub_f32_e32 v88, v88, v215
	v_sub_f32_e32 v89, v89, v215
	v_sub_f32_e32 v90, v90, v215
	v_sub_f32_e32 v91, v91, v215
	v_sub_f32_e32 v92, v92, v215
	v_sub_f32_e32 v93, v93, v215
	v_sub_f32_e32 v94, v94, v215
	v_sub_f32_e32 v95, v95, v215
